# softmax rescale branch on the all-lanes ballot directly; new-max/alpha/exp and l rescale only on the rare path
# speedup vs baseline: 1.0172x; 1.0031x over previous
.LBB0_513:
	s_lshl_b32 s4, s76, 14
	v_add3_u32 v236, s4, v221, v220
	ds_read_b128 v[192:195], v236
	ds_read_b128 v[196:199], v236 offset:8192
	v_add3_u32 v236, s4, v222, v220
	ds_read_b128 v[200:203], v236
	ds_read_b128 v[204:207], v236 offset:8192
	v_add3_u32 v236, s4, v223, v220
	ds_read_b128 v[240:243], v236
	ds_read_b128 v[244:247], v236 offset:8192
	v_add3_u32 v236, s4, v224, v220
	ds_read_b128 v[248:251], v236
	ds_read_b128 v[252:255], v236 offset:8192
	s_waitcnt lgkmcnt(7)
	v_mfma_f32_32x32x16_bf16 v[144:159], v[192:195], v[160:163], 0
	s_waitcnt lgkmcnt(6)
	v_mfma_f32_32x32x16_bf16 v[128:143], v[196:199], v[160:163], 0
	v_add3_u32 v236, s4, v225, v220
	ds_read_b128 v[192:195], v236
	ds_read_b128 v[196:199], v236 offset:8192
	s_waitcnt lgkmcnt(7)
	v_mfma_f32_32x32x16_bf16 v[144:159], v[200:203], v[164:167], v[144:159]
	s_waitcnt lgkmcnt(6)
	v_mfma_f32_32x32x16_bf16 v[128:143], v[204:207], v[164:167], v[128:143]
	v_add3_u32 v236, s4, v227, v220
	ds_read_b128 v[200:203], v236
	ds_read_b128 v[204:207], v236 offset:8192
	s_waitcnt lgkmcnt(7)
	v_mfma_f32_32x32x16_bf16 v[144:159], v[240:243], v[168:171], v[144:159]
	s_waitcnt lgkmcnt(6)
	v_mfma_f32_32x32x16_bf16 v[128:143], v[244:247], v[168:171], v[128:143]
	v_add3_u32 v236, s4, v228, v220
	ds_read_b128 v[240:243], v236
	ds_read_b128 v[244:247], v236 offset:8192
	s_waitcnt lgkmcnt(7)
	v_mfma_f32_32x32x16_bf16 v[144:159], v[248:251], v[172:175], v[144:159]
	s_waitcnt lgkmcnt(6)
	v_mfma_f32_32x32x16_bf16 v[128:143], v[252:255], v[172:175], v[128:143]
	v_add3_u32 v236, s4, v229, v220
	ds_read_b128 v[248:251], v236
	ds_read_b128 v[252:255], v236 offset:8192
	s_waitcnt lgkmcnt(7)
	v_mfma_f32_32x32x16_bf16 v[144:159], v[192:195], v[176:179], v[144:159]
	s_waitcnt lgkmcnt(6)
	v_mfma_f32_32x32x16_bf16 v[128:143], v[196:199], v[176:179], v[128:143]
	s_waitcnt lgkmcnt(5)
	v_mfma_f32_32x32x16_bf16 v[144:159], v[200:203], v[180:183], v[144:159]
	s_waitcnt lgkmcnt(4)
	v_mfma_f32_32x32x16_bf16 v[128:143], v[204:207], v[180:183], v[128:143]
	s_waitcnt lgkmcnt(3)
	v_mfma_f32_32x32x16_bf16 v[144:159], v[240:243], v[184:187], v[144:159]
	s_waitcnt lgkmcnt(2)
	v_mfma_f32_32x32x16_bf16 v[128:143], v[244:247], v[184:187], v[128:143]
	s_waitcnt lgkmcnt(1)
	v_mfma_f32_32x32x16_bf16 v[144:159], v[248:251], v[188:191], v[144:159]
	s_waitcnt lgkmcnt(0)
	v_mfma_f32_32x32x16_bf16 v[128:143], v[252:255], v[188:191], v[128:143]
	s_nop 9
	v_max_f32_e32 v192, v144, v145
	v_max3_f32 v192, v192, v146, v147
	v_max3_f32 v192, v192, v148, v149
	v_max3_f32 v192, v192, v150, v151
	v_max3_f32 v192, v192, v152, v153
	v_max3_f32 v192, v192, v154, v155
	v_max3_f32 v192, v192, v156, v157
	v_max3_f32 v192, v192, v158, v159
	v_max3_f32 v192, v192, v128, v129
	v_max3_f32 v192, v192, v130, v131
	v_max3_f32 v192, v192, v132, v133
	v_max3_f32 v192, v192, v134, v135
	v_max3_f32 v192, v192, v136, v137
	v_max3_f32 v192, v192, v138, v139
	v_max3_f32 v192, v192, v140, v141
	v_max3_f32 v192, v192, v142, v143
	v_mov_b32_e32 v193, v192
	s_nop 1
	v_permlane32_swap_b32_e32 v192, v193
	v_max_f32_e32 v192, v192, v193
	v_sub_f32_e32 v193, v192, v231
	v_cmp_ge_f32_e32 vcc, s38, v193
	s_cmp_eq_u64 vcc, exec
	s_cbranch_scc1 .LBB0_517
	v_max_f32_e32 v234, v231, v192
	v_sub_f32_e32 v192, v231, v234
	v_mul_f32_e32 v192, 0x3e0293ee, v192
	v_exp_f32_e32 v233, v192
	v_mov_b32_e32 v231, v234
	v_mul_f32_e32 v237, 0xbe0293ee, v234
	v_mul_f32_e32 v232, v232, v233
	s_and_saveexec_b64 s[24:25], s[0:1]
	ds_write_b32 v226, v233 offset:128
	s_or_b64 exec, exec, s[24:25]
	s_waitcnt lgkmcnt(0)
	v_add_u32_e32 v192, s21, v210
	ds_read_b128 v[204:207], v192 offset:224
	ds_read_b128 v[200:203], v192 offset:192
	ds_read_b128 v[196:199], v192 offset:160
	ds_read_b128 v[192:195], v192 offset:128
	s_waitcnt lgkmcnt(3)
	v_pk_mul_f32 v[12:13], v[12:13], v[204:205]
	s_waitcnt lgkmcnt(2)
	v_pk_mul_f32 v[8:9], v[8:9], v[200:201]
	s_waitcnt lgkmcnt(1)
	v_pk_mul_f32 v[4:5], v[4:5], v[196:197]
	v_pk_mul_f32 v[14:15], v[14:15], v[206:207]
	v_pk_mul_f32 v[10:11], v[10:11], v[202:203]
	v_pk_mul_f32 v[6:7], v[6:7], v[198:199]
	s_waitcnt lgkmcnt(0)
	v_pk_mul_f32 v[2:3], v[2:3], v[194:195]
	v_pk_mul_f32 v[0:1], v[0:1], v[192:193]
	v_pk_mul_f32 v[124:125], v[124:125], v[204:205]
	v_pk_mul_f32 v[120:121], v[120:121], v[200:201]
	v_pk_mul_f32 v[116:117], v[116:117], v[196:197]
	v_pk_mul_f32 v[126:127], v[126:127], v[206:207]
	v_pk_mul_f32 v[122:123], v[122:123], v[202:203]
	v_pk_mul_f32 v[118:119], v[118:119], v[198:199]
	v_pk_mul_f32 v[114:115], v[114:115], v[194:195]
	v_pk_mul_f32 v[112:113], v[112:113], v[192:193]
	v_pk_mul_f32 v[108:109], v[108:109], v[204:205]
	v_pk_mul_f32 v[104:105], v[104:105], v[200:201]
	v_pk_mul_f32 v[100:101], v[100:101], v[196:197]
	v_pk_mul_f32 v[110:111], v[110:111], v[206:207]
	v_pk_mul_f32 v[106:107], v[106:107], v[202:203]
	v_pk_mul_f32 v[102:103], v[102:103], v[198:199]
	v_pk_mul_f32 v[98:99], v[98:99], v[194:195]
	v_pk_mul_f32 v[96:97], v[96:97], v[192:193]
	v_pk_mul_f32 v[92:93], v[92:93], v[204:205]
	v_pk_mul_f32 v[88:89], v[88:89], v[200:201]
	v_pk_mul_f32 v[84:85], v[84:85], v[196:197]
	v_pk_mul_f32 v[94:95], v[94:95], v[206:207]
	v_pk_mul_f32 v[90:91], v[90:91], v[202:203]
	v_pk_mul_f32 v[86:87], v[86:87], v[198:199]
	v_pk_mul_f32 v[82:83], v[82:83], v[194:195]
	v_pk_mul_f32 v[80:81], v[80:81], v[192:193]
	v_pk_mul_f32 v[76:77], v[76:77], v[204:205]
	v_pk_mul_f32 v[72:73], v[72:73], v[200:201]
	v_pk_mul_f32 v[68:69], v[68:69], v[196:197]
	v_pk_mul_f32 v[78:79], v[78:79], v[206:207]
	v_pk_mul_f32 v[74:75], v[74:75], v[202:203]
	v_pk_mul_f32 v[70:71], v[70:71], v[198:199]
	v_pk_mul_f32 v[66:67], v[66:67], v[194:195]
	v_pk_mul_f32 v[64:65], v[64:65], v[192:193]
	v_pk_mul_f32 v[60:61], v[60:61], v[204:205]
	v_pk_mul_f32 v[56:57], v[56:57], v[200:201]
	v_pk_mul_f32 v[52:53], v[52:53], v[196:197]
	v_pk_mul_f32 v[62:63], v[62:63], v[206:207]
	v_pk_mul_f32 v[58:59], v[58:59], v[202:203]
	v_pk_mul_f32 v[54:55], v[54:55], v[198:199]
	v_pk_mul_f32 v[50:51], v[50:51], v[194:195]
	v_pk_mul_f32 v[48:49], v[48:49], v[192:193]
	v_pk_mul_f32 v[44:45], v[44:45], v[204:205]
	v_pk_mul_f32 v[40:41], v[40:41], v[200:201]
	v_pk_mul_f32 v[36:37], v[36:37], v[196:197]
	v_pk_mul_f32 v[46:47], v[46:47], v[206:207]
	v_pk_mul_f32 v[42:43], v[42:43], v[202:203]
	v_pk_mul_f32 v[38:39], v[38:39], v[198:199]
	v_pk_mul_f32 v[34:35], v[34:35], v[194:195]
	v_pk_mul_f32 v[32:33], v[32:33], v[192:193]
	v_pk_mul_f32 v[28:29], v[28:29], v[204:205]
	v_pk_mul_f32 v[24:25], v[24:25], v[200:201]
	v_pk_mul_f32 v[20:21], v[20:21], v[196:197]
	v_pk_mul_f32 v[30:31], v[30:31], v[206:207]
	v_pk_mul_f32 v[26:27], v[26:27], v[202:203]
	v_pk_mul_f32 v[22:23], v[22:23], v[198:199]
	v_pk_mul_f32 v[18:19], v[18:19], v[194:195]
	v_pk_mul_f32 v[16:17], v[16:17], v[192:193]
.LBB0_517:
	v_fmamk_f32 v144, v144, 0x3e0293ee, v237
	v_fmamk_f32 v145, v145, 0x3e0293ee, v237
	v_fmamk_f32 v146, v146, 0x3e0293ee, v237
	v_fmamk_f32 v147, v147, 0x3e0293ee, v237
	v_fmamk_f32 v148, v148, 0x3e0293ee, v237
	v_fmamk_f32 v149, v149, 0x3e0293ee, v237
	v_fmamk_f32 v150, v150, 0x3e0293ee, v237
	v_fmamk_f32 v151, v151, 0x3e0293ee, v237
	v_fmamk_f32 v152, v152, 0x3e0293ee, v237
	v_fmamk_f32 v153, v153, 0x3e0293ee, v237
	v_fmamk_f32 v154, v154, 0x3e0293ee, v237
	v_fmamk_f32 v155, v155, 0x3e0293ee, v237
	v_fmamk_f32 v156, v156, 0x3e0293ee, v237
	v_fmamk_f32 v157, v157, 0x3e0293ee, v237
	v_fmamk_f32 v158, v158, 0x3e0293ee, v237
	v_fmamk_f32 v159, v159, 0x3e0293ee, v237
	v_fmamk_f32 v128, v128, 0x3e0293ee, v237
	v_fmamk_f32 v129, v129, 0x3e0293ee, v237
	v_fmamk_f32 v130, v130, 0x3e0293ee, v237
	v_fmamk_f32 v131, v131, 0x3e0293ee, v237
	v_fmamk_f32 v132, v132, 0x3e0293ee, v237
	v_fmamk_f32 v133, v133, 0x3e0293ee, v237
	v_fmamk_f32 v134, v134, 0x3e0293ee, v237
	v_fmamk_f32 v135, v135, 0x3e0293ee, v237
	v_fmamk_f32 v136, v136, 0x3e0293ee, v237
	v_fmamk_f32 v137, v137, 0x3e0293ee, v237
	v_fmamk_f32 v138, v138, 0x3e0293ee, v237
	v_fmamk_f32 v139, v139, 0x3e0293ee, v237
	v_fmamk_f32 v140, v140, 0x3e0293ee, v237
	v_fmamk_f32 v141, v141, 0x3e0293ee, v237
	v_fmamk_f32 v142, v142, 0x3e0293ee, v237
	v_fmamk_f32 v192, v143, 0x3e0293ee, v237
	v_exp_f32_e32 v143, v144
	v_exp_f32_e32 v145, v145
	v_exp_f32_e32 v146, v146
	v_exp_f32_e32 v147, v147
	v_exp_f32_e32 v148, v148
	v_exp_f32_e32 v193, v128
	v_exp_f32_e32 v149, v149
	v_add_f32_e32 v128, v145, v143
	v_exp_f32_e32 v150, v150
	v_add_f32_e32 v128, v146, v128
	v_exp_f32_e32 v151, v151
	v_add_f32_e32 v128, v147, v128
	v_exp_f32_e32 v152, v152
	v_add_f32_e32 v128, v148, v128
	v_exp_f32_e32 v153, v153
	v_add_f32_e32 v128, v149, v128
	v_exp_f32_e32 v154, v154
	v_add_f32_e32 v128, v150, v128
	v_exp_f32_e32 v155, v155
	v_add_f32_e32 v128, v151, v128
	v_exp_f32_e32 v156, v156
	v_add_f32_e32 v128, v152, v128
	v_exp_f32_e32 v157, v157
	v_add_f32_e32 v128, v153, v128
	v_exp_f32_e32 v158, v158
	v_add_f32_e32 v128, v154, v128
	v_exp_f32_e32 v159, v159
	v_add_f32_e32 v128, v155, v128
	v_add_f32_e32 v128, v156, v128
	v_exp_f32_e32 v194, v129
	v_add_f32_e32 v128, v157, v128
	v_exp_f32_e32 v195, v130
	v_add_f32_e32 v128, v158, v128
	v_exp_f32_e32 v196, v131
	v_add_f32_e32 v128, v159, v128
	v_exp_f32_e32 v197, v132
	v_add_f32_e32 v128, v193, v128
	v_exp_f32_e32 v198, v133
	v_add_f32_e32 v128, v194, v128
	v_exp_f32_e32 v199, v134
	v_add_f32_e32 v128, v195, v128
	v_exp_f32_e32 v135, v135
	v_add_f32_e32 v128, v196, v128
	v_exp_f32_e32 v200, v136
	v_add_f32_e32 v128, v197, v128
	v_exp_f32_e32 v201, v137
	v_add_f32_e32 v128, v198, v128
	v_exp_f32_e32 v202, v138
	v_add_f32_e32 v128, v199, v128
	v_exp_f32_e32 v203, v139
	v_add_f32_e32 v128, v135, v128
	v_exp_f32_e32 v204, v140
	v_add_f32_e32 v128, v200, v128
	v_exp_f32_e32 v205, v141
	v_add_f32_e32 v128, v201, v128
	v_exp_f32_e32 v206, v142
	v_add_f32_e32 v128, v202, v128
	v_exp_f32_e32 v192, v192
	v_add_f32_e32 v128, v203, v128
	v_add_f32_e32 v128, v204, v128
	v_add_f32_e32 v128, v205, v128
	v_add_f32_e32 v128, v206, v128
	v_add_f32_e32 v128, v192, v128
	v_add_f32_e32 v144, v232, v128
	v_cvt_pk_bf16_f32 v128, v143, v145
	v_cvt_pk_bf16_f32 v129, v146, v147
	v_cvt_pk_bf16_f32 v130, v148, v149
	v_cvt_pk_bf16_f32 v131, v150, v151
	v_cvt_pk_bf16_f32 v136, v152, v153
	v_cvt_pk_bf16_f32 v137, v154, v155
	v_cvt_pk_bf16_f32 v138, v156, v157
	v_cvt_pk_bf16_f32 v139, v158, v159
	v_cvt_pk_bf16_f32 v132, v193, v194
	v_cvt_pk_bf16_f32 v133, v195, v196
	v_cvt_pk_bf16_f32 v134, v197, v198
	v_cvt_pk_bf16_f32 v135, v199, v135
	v_cvt_pk_bf16_f32 v140, v200, v201
	v_cvt_pk_bf16_f32 v141, v202, v203
	v_cvt_pk_bf16_f32 v142, v204, v205
	v_cvt_pk_bf16_f32 v143, v206, v192
	v_lshl_add_u32 v145, s76, 15, v230
	ds_read_b64_tr_b16 v[146:147], v145 offset:0
	ds_read_b64_tr_b16 v[148:149], v145 offset:4096
	ds_read_b64_tr_b16 v[150:151], v145 offset:512
	ds_read_b64_tr_b16 v[152:153], v145 offset:4608
	ds_read_b64_tr_b16 v[154:155], v145 offset:1024
	ds_read_b64_tr_b16 v[156:157], v145 offset:5120
	ds_read_b64_tr_b16 v[192:193], v145 offset:1536
	ds_read_b64_tr_b16 v[194:195], v145 offset:5632
	ds_read_b64_tr_b16 v[196:197], v145 offset:2048
	ds_read_b64_tr_b16 v[198:199], v145 offset:6144
	ds_read_b64_tr_b16 v[200:201], v145 offset:2560
	ds_read_b64_tr_b16 v[202:203], v145 offset:6656
	ds_read_b64_tr_b16 v[204:205], v145 offset:3072
	ds_read_b64_tr_b16 v[206:207], v145 offset:7168
	s_waitcnt lgkmcnt(12)
	s_nop 0
	v_mfma_f32_32x32x16_bf16 v[0:15], v[128:131], v[146:149], v[0:15]
	ds_read_b64_tr_b16 v[232:233], v145 offset:3584
	ds_read_b64_tr_b16 v[234:235], v145 offset:7680
	s_waitcnt lgkmcnt(12)
	v_mfma_f32_32x32x16_bf16 v[112:127], v[128:131], v[150:153], v[112:127]
	ds_read_b64_tr_b16 v[146:147], v145 offset:8192
	ds_read_b64_tr_b16 v[148:149], v145 offset:12288
	s_waitcnt lgkmcnt(12)
	v_mfma_f32_32x32x16_bf16 v[96:111], v[128:131], v[154:157], v[96:111]
	ds_read_b64_tr_b16 v[150:151], v145 offset:8704
	ds_read_b64_tr_b16 v[152:153], v145 offset:12800
	s_waitcnt lgkmcnt(12)
	v_mfma_f32_32x32x16_bf16 v[80:95], v[128:131], v[192:195], v[80:95]
	ds_read_b64_tr_b16 v[154:155], v145 offset:9216
	ds_read_b64_tr_b16 v[156:157], v145 offset:13312
	s_waitcnt lgkmcnt(12)
	v_mfma_f32_32x32x16_bf16 v[64:79], v[128:131], v[196:199], v[64:79]
	ds_read_b64_tr_b16 v[192:193], v145 offset:9728
	ds_read_b64_tr_b16 v[194:195], v145 offset:13824
	s_waitcnt lgkmcnt(12)
	v_mfma_f32_32x32x16_bf16 v[48:63], v[128:131], v[200:203], v[48:63]
	ds_read_b64_tr_b16 v[196:197], v145 offset:10240
	ds_read_b64_tr_b16 v[198:199], v145 offset:14336
	s_waitcnt lgkmcnt(12)
	v_mfma_f32_32x32x16_bf16 v[32:47], v[128:131], v[204:207], v[32:47]
	ds_read_b64_tr_b16 v[200:201], v145 offset:10752
	ds_read_b64_tr_b16 v[202:203], v145 offset:14848
	s_waitcnt lgkmcnt(12)
	v_mfma_f32_32x32x16_bf16 v[16:31], v[128:131], v[232:235], v[16:31]
	ds_read_b64_tr_b16 v[204:205], v145 offset:11264
	ds_read_b64_tr_b16 v[206:207], v145 offset:15360
	s_waitcnt lgkmcnt(12)
	v_mfma_f32_32x32x16_bf16 v[0:15], v[136:139], v[146:149], v[0:15]
	ds_read_b64_tr_b16 v[232:233], v145 offset:11776
	ds_read_b64_tr_b16 v[234:235], v145 offset:15872
	s_waitcnt lgkmcnt(12)
	v_mfma_f32_32x32x16_bf16 v[112:127], v[136:139], v[150:153], v[112:127]
	ds_read_b64_tr_b16 v[146:147], v145 offset:16384
	ds_read_b64_tr_b16 v[148:149], v145 offset:20480
	s_waitcnt lgkmcnt(12)
	v_mfma_f32_32x32x16_bf16 v[96:111], v[136:139], v[154:157], v[96:111]
	ds_read_b64_tr_b16 v[150:151], v145 offset:16896
	ds_read_b64_tr_b16 v[152:153], v145 offset:20992
	s_waitcnt lgkmcnt(12)
	v_mfma_f32_32x32x16_bf16 v[80:95], v[136:139], v[192:195], v[80:95]
	ds_read_b64_tr_b16 v[154:155], v145 offset:17408
	ds_read_b64_tr_b16 v[156:157], v145 offset:21504
	s_waitcnt lgkmcnt(12)
	v_mfma_f32_32x32x16_bf16 v[64:79], v[136:139], v[196:199], v[64:79]
	ds_read_b64_tr_b16 v[192:193], v145 offset:17920
	ds_read_b64_tr_b16 v[194:195], v145 offset:22016
	s_waitcnt lgkmcnt(12)
	v_mfma_f32_32x32x16_bf16 v[48:63], v[136:139], v[200:203], v[48:63]
	ds_read_b64_tr_b16 v[196:197], v145 offset:18432
	ds_read_b64_tr_b16 v[198:199], v145 offset:22528
	s_waitcnt lgkmcnt(12)
	v_mfma_f32_32x32x16_bf16 v[32:47], v[136:139], v[204:207], v[32:47]
	ds_read_b64_tr_b16 v[200:201], v145 offset:18944
	ds_read_b64_tr_b16 v[202:203], v145 offset:23040
	s_waitcnt lgkmcnt(12)
	v_mfma_f32_32x32x16_bf16 v[16:31], v[136:139], v[232:235], v[16:31]
	ds_read_b64_tr_b16 v[204:205], v145 offset:19456
	ds_read_b64_tr_b16 v[206:207], v145 offset:23552
	s_waitcnt lgkmcnt(12)
	v_mfma_f32_32x32x16_bf16 v[0:15], v[132:135], v[146:149], v[0:15]
	ds_read_b64_tr_b16 v[232:233], v145 offset:19968
	ds_read_b64_tr_b16 v[234:235], v145 offset:24064
	s_waitcnt lgkmcnt(12)
	v_mfma_f32_32x32x16_bf16 v[112:127], v[132:135], v[150:153], v[112:127]
	ds_read_b64_tr_b16 v[146:147], v145 offset:24576
	ds_read_b64_tr_b16 v[148:149], v145 offset:28672
	s_waitcnt lgkmcnt(12)
	v_mfma_f32_32x32x16_bf16 v[96:111], v[132:135], v[154:157], v[96:111]
	ds_read_b64_tr_b16 v[150:151], v145 offset:25088
	ds_read_b64_tr_b16 v[152:153], v145 offset:29184
	s_waitcnt lgkmcnt(12)
	v_mfma_f32_32x32x16_bf16 v[80:95], v[132:135], v[192:195], v[80:95]
	ds_read_b64_tr_b16 v[154:155], v145 offset:25600
	ds_read_b64_tr_b16 v[156:157], v145 offset:29696
	s_waitcnt lgkmcnt(12)
	v_mfma_f32_32x32x16_bf16 v[64:79], v[132:135], v[196:199], v[64:79]
	ds_read_b64_tr_b16 v[192:193], v145 offset:26112
	ds_read_b64_tr_b16 v[194:195], v145 offset:30208
	s_waitcnt lgkmcnt(12)
	v_mfma_f32_32x32x16_bf16 v[48:63], v[132:135], v[200:203], v[48:63]
	ds_read_b64_tr_b16 v[196:197], v145 offset:26624
	ds_read_b64_tr_b16 v[198:199], v145 offset:30720
	s_waitcnt lgkmcnt(12)
	v_mfma_f32_32x32x16_bf16 v[32:47], v[132:135], v[204:207], v[32:47]
	ds_read_b64_tr_b16 v[200:201], v145 offset:27136
	ds_read_b64_tr_b16 v[202:203], v145 offset:31232
	s_waitcnt lgkmcnt(12)
	v_mfma_f32_32x32x16_bf16 v[16:31], v[132:135], v[232:235], v[16:31]
	ds_read_b64_tr_b16 v[204:205], v145 offset:27648
	ds_read_b64_tr_b16 v[206:207], v145 offset:31744
	s_waitcnt lgkmcnt(12)
	v_mfma_f32_32x32x16_bf16 v[0:15], v[140:143], v[146:149], v[0:15]
	ds_read_b64_tr_b16 v[232:233], v145 offset:28160
	ds_read_b64_tr_b16 v[234:235], v145 offset:32256
	s_waitcnt lgkmcnt(12)
	v_mfma_f32_32x32x16_bf16 v[112:127], v[140:143], v[150:153], v[112:127]
	s_waitcnt lgkmcnt(10)
	v_mfma_f32_32x32x16_bf16 v[96:111], v[140:143], v[154:157], v[96:111]
	s_waitcnt lgkmcnt(8)
	v_mfma_f32_32x32x16_bf16 v[80:95], v[140:143], v[192:195], v[80:95]
	s_waitcnt lgkmcnt(6)
	v_mfma_f32_32x32x16_bf16 v[64:79], v[140:143], v[196:199], v[64:79]
	s_add_i32 s4, s76, 1
	s_cmp_lg_u32 s76, 2
	s_cselect_b32 s76, s4, 0
	s_add_i32 s4, s74, 1
	s_cmp_lg_u32 s74, 2
	s_cselect_b32 s74, s4, 0
	s_add_u32 s22, s22, 0x20000
	s_waitcnt lgkmcnt(4)
	v_mfma_f32_32x32x16_bf16 v[48:63], v[140:143], v[200:203], v[48:63]
	s_addc_u32 s23, s23, 0
	s_add_i32 s86, s86, 1
	s_cmp_eq_u32 s22, 0x800000
	s_waitcnt lgkmcnt(2)
	v_mfma_f32_32x32x16_bf16 v[32:47], v[140:143], v[204:207], v[32:47]
	s_waitcnt lgkmcnt(0)
	v_mfma_f32_32x32x16_bf16 v[16:31], v[140:143], v[232:235], v[16:31]
	s_cbranch_scc1 .LBB0_521
	v_mov_b32_e32 v232, v144
	s_cmp_eq_u32 s22, 0x7e0000
	s_mov_b64 s[4:5], -1
	s_cbranch_scc1 .LBB0_510

.LBB0_906:
	s_lshl_b32 s4, s80, 14
	v_add3_u32 v236, s4, v221, v220
	ds_read_b128 v[192:195], v236
	ds_read_b128 v[196:199], v236 offset:8192
	v_add3_u32 v236, s4, v222, v220
	ds_read_b128 v[200:203], v236
	ds_read_b128 v[204:207], v236 offset:8192
	v_add3_u32 v236, s4, v223, v220
	ds_read_b128 v[240:243], v236
	ds_read_b128 v[244:247], v236 offset:8192
	v_add3_u32 v236, s4, v225, v220
	ds_read_b128 v[248:251], v236
	ds_read_b128 v[252:255], v236 offset:8192
	s_waitcnt lgkmcnt(7)
	v_mfma_f32_32x32x16_bf16 v[144:159], v[192:195], v[160:163], 0
	s_waitcnt lgkmcnt(6)
	v_mfma_f32_32x32x16_bf16 v[128:143], v[196:199], v[160:163], 0
	v_add3_u32 v236, s4, v226, v220
	ds_read_b128 v[192:195], v236
	ds_read_b128 v[196:199], v236 offset:8192
	s_waitcnt lgkmcnt(7)
	v_mfma_f32_32x32x16_bf16 v[144:159], v[200:203], v[164:167], v[144:159]
	s_waitcnt lgkmcnt(6)
	v_mfma_f32_32x32x16_bf16 v[128:143], v[204:207], v[164:167], v[128:143]
	v_add3_u32 v236, s4, v227, v220
	ds_read_b128 v[200:203], v236
	ds_read_b128 v[204:207], v236 offset:8192
	s_waitcnt lgkmcnt(7)
	v_mfma_f32_32x32x16_bf16 v[144:159], v[240:243], v[168:171], v[144:159]
	s_waitcnt lgkmcnt(6)
	v_mfma_f32_32x32x16_bf16 v[128:143], v[244:247], v[168:171], v[128:143]
	v_add3_u32 v236, s4, v228, v220
	ds_read_b128 v[240:243], v236
	ds_read_b128 v[244:247], v236 offset:8192
	s_waitcnt lgkmcnt(7)
	v_mfma_f32_32x32x16_bf16 v[144:159], v[248:251], v[172:175], v[144:159]
	s_waitcnt lgkmcnt(6)
	v_mfma_f32_32x32x16_bf16 v[128:143], v[252:255], v[172:175], v[128:143]
	v_add3_u32 v236, s4, v229, v220
	ds_read_b128 v[248:251], v236
	ds_read_b128 v[252:255], v236 offset:8192
	s_waitcnt lgkmcnt(7)
	v_mfma_f32_32x32x16_bf16 v[144:159], v[192:195], v[176:179], v[144:159]
	s_waitcnt lgkmcnt(6)
	v_mfma_f32_32x32x16_bf16 v[128:143], v[196:199], v[176:179], v[128:143]
	s_waitcnt lgkmcnt(5)
	v_mfma_f32_32x32x16_bf16 v[144:159], v[200:203], v[180:183], v[144:159]
	s_waitcnt lgkmcnt(4)
	v_mfma_f32_32x32x16_bf16 v[128:143], v[204:207], v[180:183], v[128:143]
	s_waitcnt lgkmcnt(3)
	v_mfma_f32_32x32x16_bf16 v[144:159], v[240:243], v[184:187], v[144:159]
	s_waitcnt lgkmcnt(2)
	v_mfma_f32_32x32x16_bf16 v[128:143], v[244:247], v[184:187], v[128:143]
	s_waitcnt lgkmcnt(1)
	v_mfma_f32_32x32x16_bf16 v[144:159], v[248:251], v[188:191], v[144:159]
	s_waitcnt lgkmcnt(0)
	v_mfma_f32_32x32x16_bf16 v[128:143], v[252:255], v[188:191], v[128:143]
	v_max_f32_e32 v194, v231, v231
	s_nop 9
	v_max_f32_e32 v192, v144, v145
	v_max3_f32 v192, v192, v146, v147
	v_max3_f32 v192, v192, v148, v149
	v_max3_f32 v192, v192, v150, v151
	v_max3_f32 v192, v192, v152, v153
	v_max3_f32 v192, v192, v154, v155
	v_max3_f32 v192, v192, v156, v157
	v_max3_f32 v192, v192, v158, v159
	v_max3_f32 v192, v192, v128, v129
	v_max3_f32 v192, v192, v130, v131
	v_max3_f32 v192, v192, v132, v133
	v_max3_f32 v192, v192, v134, v135
	v_max3_f32 v192, v192, v136, v137
	v_max3_f32 v192, v192, v138, v139
	v_max3_f32 v192, v192, v140, v141
	v_max3_f32 v192, v192, v142, v143
	v_mov_b32_e32 v193, v192
	s_nop 1
	v_permlane32_swap_b32_e32 v192, v193
	v_max_f32_e32 v192, v192, v193
	v_sub_f32_e32 v193, v192, v231
	v_cmp_ge_f32_e32 vcc, s42, v193
	s_cmp_eq_u64 vcc, exec
	s_cbranch_scc1 .LBB0_910
	v_max_f32_e32 v234, v194, v192
	v_sub_f32_e32 v192, v231, v234
	v_mul_f32_e32 v192, 0x3e0293ee, v192
	v_exp_f32_e32 v233, v192
	v_mov_b32_e32 v231, v234
	v_mul_f32_e32 v237, 0xbe0293ee, v234
	v_mul_f32_e32 v232, v232, v233
	s_and_saveexec_b64 s[24:25], s[0:1]
	ds_write_b32 v224, v233 offset:128
	s_or_b64 exec, exec, s[24:25]
	s_waitcnt lgkmcnt(0)
	v_add_u32_e32 v192, s21, v210
	ds_read_b128 v[204:207], v192 offset:224
	ds_read_b128 v[200:203], v192 offset:192
	ds_read_b128 v[196:199], v192 offset:160
	ds_read_b128 v[192:195], v192 offset:128
	s_waitcnt lgkmcnt(3)
	v_pk_mul_f32 v[12:13], v[12:13], v[204:205]
	s_waitcnt lgkmcnt(2)
	v_pk_mul_f32 v[8:9], v[8:9], v[200:201]
	s_waitcnt lgkmcnt(1)
	v_pk_mul_f32 v[4:5], v[4:5], v[196:197]
	v_pk_mul_f32 v[14:15], v[14:15], v[206:207]
	v_pk_mul_f32 v[10:11], v[10:11], v[202:203]
	v_pk_mul_f32 v[6:7], v[6:7], v[198:199]
	s_waitcnt lgkmcnt(0)
	v_pk_mul_f32 v[2:3], v[2:3], v[194:195]
	v_pk_mul_f32 v[0:1], v[0:1], v[192:193]
	v_pk_mul_f32 v[124:125], v[124:125], v[204:205]
	v_pk_mul_f32 v[120:121], v[120:121], v[200:201]
	v_pk_mul_f32 v[116:117], v[116:117], v[196:197]
	v_pk_mul_f32 v[126:127], v[126:127], v[206:207]
	v_pk_mul_f32 v[122:123], v[122:123], v[202:203]
	v_pk_mul_f32 v[118:119], v[118:119], v[198:199]
	v_pk_mul_f32 v[114:115], v[114:115], v[194:195]
	v_pk_mul_f32 v[112:113], v[112:113], v[192:193]
	v_pk_mul_f32 v[108:109], v[108:109], v[204:205]
	v_pk_mul_f32 v[104:105], v[104:105], v[200:201]
	v_pk_mul_f32 v[100:101], v[100:101], v[196:197]
	v_pk_mul_f32 v[110:111], v[110:111], v[206:207]
	v_pk_mul_f32 v[106:107], v[106:107], v[202:203]
	v_pk_mul_f32 v[102:103], v[102:103], v[198:199]
	v_pk_mul_f32 v[98:99], v[98:99], v[194:195]
	v_pk_mul_f32 v[96:97], v[96:97], v[192:193]
	v_pk_mul_f32 v[92:93], v[92:93], v[204:205]
	v_pk_mul_f32 v[88:89], v[88:89], v[200:201]
	v_pk_mul_f32 v[84:85], v[84:85], v[196:197]
	v_pk_mul_f32 v[94:95], v[94:95], v[206:207]
	v_pk_mul_f32 v[90:91], v[90:91], v[202:203]
	v_pk_mul_f32 v[86:87], v[86:87], v[198:199]
	v_pk_mul_f32 v[82:83], v[82:83], v[194:195]
	v_pk_mul_f32 v[80:81], v[80:81], v[192:193]
	v_pk_mul_f32 v[76:77], v[76:77], v[204:205]
	v_pk_mul_f32 v[72:73], v[72:73], v[200:201]
	v_pk_mul_f32 v[68:69], v[68:69], v[196:197]
	v_pk_mul_f32 v[78:79], v[78:79], v[206:207]
	v_pk_mul_f32 v[74:75], v[74:75], v[202:203]
	v_pk_mul_f32 v[70:71], v[70:71], v[198:199]
	v_pk_mul_f32 v[66:67], v[66:67], v[194:195]
	v_pk_mul_f32 v[64:65], v[64:65], v[192:193]
	v_pk_mul_f32 v[60:61], v[60:61], v[204:205]
	v_pk_mul_f32 v[56:57], v[56:57], v[200:201]
	v_pk_mul_f32 v[52:53], v[52:53], v[196:197]
	v_pk_mul_f32 v[62:63], v[62:63], v[206:207]
	v_pk_mul_f32 v[58:59], v[58:59], v[202:203]
	v_pk_mul_f32 v[54:55], v[54:55], v[198:199]
	v_pk_mul_f32 v[50:51], v[50:51], v[194:195]
	v_pk_mul_f32 v[48:49], v[48:49], v[192:193]
	v_pk_mul_f32 v[44:45], v[44:45], v[204:205]
	v_pk_mul_f32 v[40:41], v[40:41], v[200:201]
	v_pk_mul_f32 v[36:37], v[36:37], v[196:197]
	v_pk_mul_f32 v[46:47], v[46:47], v[206:207]
	v_pk_mul_f32 v[42:43], v[42:43], v[202:203]
	v_pk_mul_f32 v[38:39], v[38:39], v[198:199]
	v_pk_mul_f32 v[34:35], v[34:35], v[194:195]
	v_pk_mul_f32 v[32:33], v[32:33], v[192:193]
	v_pk_mul_f32 v[28:29], v[28:29], v[204:205]
	v_pk_mul_f32 v[24:25], v[24:25], v[200:201]
	v_pk_mul_f32 v[20:21], v[20:21], v[196:197]
	v_pk_mul_f32 v[30:31], v[30:31], v[206:207]
	v_pk_mul_f32 v[26:27], v[26:27], v[202:203]
	v_pk_mul_f32 v[22:23], v[22:23], v[198:199]
	v_pk_mul_f32 v[18:19], v[18:19], v[194:195]
	v_pk_mul_f32 v[16:17], v[16:17], v[192:193]
.LBB0_910:
	v_fmamk_f32 v144, v144, 0x3e0293ee, v237
	v_fmamk_f32 v145, v145, 0x3e0293ee, v237
	v_fmamk_f32 v146, v146, 0x3e0293ee, v237
	v_fmamk_f32 v147, v147, 0x3e0293ee, v237
	v_fmamk_f32 v148, v148, 0x3e0293ee, v237
	v_fmamk_f32 v149, v149, 0x3e0293ee, v237
	v_fmamk_f32 v150, v150, 0x3e0293ee, v237
	v_fmamk_f32 v151, v151, 0x3e0293ee, v237
	v_fmamk_f32 v152, v152, 0x3e0293ee, v237
	v_fmamk_f32 v153, v153, 0x3e0293ee, v237
	v_fmamk_f32 v154, v154, 0x3e0293ee, v237
	v_fmamk_f32 v155, v155, 0x3e0293ee, v237
	v_fmamk_f32 v156, v156, 0x3e0293ee, v237
	v_fmamk_f32 v157, v157, 0x3e0293ee, v237
	v_fmamk_f32 v158, v158, 0x3e0293ee, v237
	v_fmamk_f32 v159, v159, 0x3e0293ee, v237
	v_fmamk_f32 v128, v128, 0x3e0293ee, v237
	v_fmamk_f32 v129, v129, 0x3e0293ee, v237
	v_fmamk_f32 v130, v130, 0x3e0293ee, v237
	v_fmamk_f32 v131, v131, 0x3e0293ee, v237
	v_fmamk_f32 v132, v132, 0x3e0293ee, v237
	v_fmamk_f32 v133, v133, 0x3e0293ee, v237
	v_fmamk_f32 v134, v134, 0x3e0293ee, v237
	v_fmamk_f32 v135, v135, 0x3e0293ee, v237
	v_fmamk_f32 v136, v136, 0x3e0293ee, v237
	v_fmamk_f32 v137, v137, 0x3e0293ee, v237
	v_fmamk_f32 v138, v138, 0x3e0293ee, v237
	v_fmamk_f32 v139, v139, 0x3e0293ee, v237
	v_fmamk_f32 v140, v140, 0x3e0293ee, v237
	v_fmamk_f32 v141, v141, 0x3e0293ee, v237
	v_fmamk_f32 v142, v142, 0x3e0293ee, v237
	v_fmamk_f32 v192, v143, 0x3e0293ee, v237
	v_exp_f32_e32 v143, v144
	v_exp_f32_e32 v145, v145
	v_exp_f32_e32 v146, v146
	v_exp_f32_e32 v147, v147
	v_exp_f32_e32 v148, v148
	v_exp_f32_e32 v193, v128
	v_exp_f32_e32 v149, v149
	v_add_f32_e32 v128, v145, v143
	v_exp_f32_e32 v150, v150
	v_add_f32_e32 v128, v146, v128
	v_exp_f32_e32 v151, v151
	v_add_f32_e32 v128, v147, v128
	v_exp_f32_e32 v152, v152
	v_add_f32_e32 v128, v148, v128
	v_exp_f32_e32 v153, v153
	v_add_f32_e32 v128, v149, v128
	v_exp_f32_e32 v154, v154
	v_add_f32_e32 v128, v150, v128
	v_exp_f32_e32 v155, v155
	v_add_f32_e32 v128, v151, v128
	v_exp_f32_e32 v156, v156
	v_add_f32_e32 v128, v152, v128
	v_exp_f32_e32 v157, v157
	v_add_f32_e32 v128, v153, v128
	v_exp_f32_e32 v158, v158
	v_add_f32_e32 v128, v154, v128
	v_exp_f32_e32 v159, v159
	v_add_f32_e32 v128, v155, v128
	v_add_f32_e32 v128, v156, v128
	v_exp_f32_e32 v194, v129
	v_add_f32_e32 v128, v157, v128
	v_exp_f32_e32 v195, v130
	v_add_f32_e32 v128, v158, v128
	v_exp_f32_e32 v196, v131
	v_add_f32_e32 v128, v159, v128
	v_exp_f32_e32 v197, v132
	v_add_f32_e32 v128, v193, v128
	v_exp_f32_e32 v198, v133
	v_add_f32_e32 v128, v194, v128
	v_exp_f32_e32 v199, v134
	v_add_f32_e32 v128, v195, v128
	v_exp_f32_e32 v135, v135
	v_add_f32_e32 v128, v196, v128
	v_exp_f32_e32 v200, v136
	v_add_f32_e32 v128, v197, v128
	v_exp_f32_e32 v201, v137
	v_add_f32_e32 v128, v198, v128
	v_exp_f32_e32 v202, v138
	v_add_f32_e32 v128, v199, v128
	v_exp_f32_e32 v203, v139
	v_add_f32_e32 v128, v135, v128
	v_exp_f32_e32 v204, v140
	v_add_f32_e32 v128, v200, v128
	v_exp_f32_e32 v205, v141
	v_add_f32_e32 v128, v201, v128
	v_exp_f32_e32 v206, v142
	v_add_f32_e32 v128, v202, v128
	v_exp_f32_e32 v192, v192
	v_add_f32_e32 v128, v203, v128
	v_add_f32_e32 v128, v204, v128
	v_add_f32_e32 v128, v205, v128
	v_add_f32_e32 v128, v206, v128
	v_add_f32_e32 v128, v192, v128
	v_add_f32_e32 v144, v232, v128
	v_cvt_pk_bf16_f32 v128, v143, v145
	v_cvt_pk_bf16_f32 v129, v146, v147
	v_cvt_pk_bf16_f32 v130, v148, v149
	v_cvt_pk_bf16_f32 v131, v150, v151
	v_cvt_pk_bf16_f32 v136, v152, v153
	v_cvt_pk_bf16_f32 v137, v154, v155
	v_cvt_pk_bf16_f32 v138, v156, v157
	v_cvt_pk_bf16_f32 v139, v158, v159
	v_cvt_pk_bf16_f32 v132, v193, v194
	v_cvt_pk_bf16_f32 v133, v195, v196
	v_cvt_pk_bf16_f32 v134, v197, v198
	v_cvt_pk_bf16_f32 v135, v199, v135
	v_cvt_pk_bf16_f32 v140, v200, v201
	v_cvt_pk_bf16_f32 v141, v202, v203
	v_cvt_pk_bf16_f32 v142, v204, v205
	v_cvt_pk_bf16_f32 v143, v206, v192
	v_lshl_add_u32 v145, s80, 15, v230
	ds_read_b64_tr_b16 v[146:147], v145 offset:0
	ds_read_b64_tr_b16 v[148:149], v145 offset:4096
	ds_read_b64_tr_b16 v[150:151], v145 offset:512
	ds_read_b64_tr_b16 v[152:153], v145 offset:4608
	ds_read_b64_tr_b16 v[154:155], v145 offset:1024
	ds_read_b64_tr_b16 v[156:157], v145 offset:5120
	ds_read_b64_tr_b16 v[192:193], v145 offset:1536
	ds_read_b64_tr_b16 v[194:195], v145 offset:5632
	ds_read_b64_tr_b16 v[196:197], v145 offset:2048
	ds_read_b64_tr_b16 v[198:199], v145 offset:6144
	ds_read_b64_tr_b16 v[200:201], v145 offset:2560
	ds_read_b64_tr_b16 v[202:203], v145 offset:6656
	ds_read_b64_tr_b16 v[204:205], v145 offset:3072
	ds_read_b64_tr_b16 v[206:207], v145 offset:7168
	s_waitcnt lgkmcnt(12)
	s_nop 0
	v_mfma_f32_32x32x16_bf16 v[0:15], v[128:131], v[146:149], v[0:15]
	ds_read_b64_tr_b16 v[232:233], v145 offset:3584
	ds_read_b64_tr_b16 v[234:235], v145 offset:7680
	s_waitcnt lgkmcnt(12)
	v_mfma_f32_32x32x16_bf16 v[112:127], v[128:131], v[150:153], v[112:127]
	ds_read_b64_tr_b16 v[146:147], v145 offset:8192
	ds_read_b64_tr_b16 v[148:149], v145 offset:12288
	s_waitcnt lgkmcnt(12)
	v_mfma_f32_32x32x16_bf16 v[96:111], v[128:131], v[154:157], v[96:111]
	ds_read_b64_tr_b16 v[150:151], v145 offset:8704
	ds_read_b64_tr_b16 v[152:153], v145 offset:12800
	s_waitcnt lgkmcnt(12)
	v_mfma_f32_32x32x16_bf16 v[80:95], v[128:131], v[192:195], v[80:95]
	ds_read_b64_tr_b16 v[154:155], v145 offset:9216
	ds_read_b64_tr_b16 v[156:157], v145 offset:13312
	s_waitcnt lgkmcnt(12)
	v_mfma_f32_32x32x16_bf16 v[64:79], v[128:131], v[196:199], v[64:79]
	ds_read_b64_tr_b16 v[192:193], v145 offset:9728
	ds_read_b64_tr_b16 v[194:195], v145 offset:13824
	s_waitcnt lgkmcnt(12)
	v_mfma_f32_32x32x16_bf16 v[48:63], v[128:131], v[200:203], v[48:63]
	ds_read_b64_tr_b16 v[196:197], v145 offset:10240
	ds_read_b64_tr_b16 v[198:199], v145 offset:14336
	s_waitcnt lgkmcnt(12)
	v_mfma_f32_32x32x16_bf16 v[32:47], v[128:131], v[204:207], v[32:47]
	ds_read_b64_tr_b16 v[200:201], v145 offset:10752
	ds_read_b64_tr_b16 v[202:203], v145 offset:14848
	s_waitcnt lgkmcnt(12)
	v_mfma_f32_32x32x16_bf16 v[16:31], v[128:131], v[232:235], v[16:31]
	ds_read_b64_tr_b16 v[204:205], v145 offset:11264
	ds_read_b64_tr_b16 v[206:207], v145 offset:15360
	s_waitcnt lgkmcnt(12)
	v_mfma_f32_32x32x16_bf16 v[0:15], v[136:139], v[146:149], v[0:15]
	ds_read_b64_tr_b16 v[232:233], v145 offset:11776
	ds_read_b64_tr_b16 v[234:235], v145 offset:15872
	s_waitcnt lgkmcnt(12)
	v_mfma_f32_32x32x16_bf16 v[112:127], v[136:139], v[150:153], v[112:127]
	ds_read_b64_tr_b16 v[146:147], v145 offset:16384
	ds_read_b64_tr_b16 v[148:149], v145 offset:20480
	s_waitcnt lgkmcnt(12)
	v_mfma_f32_32x32x16_bf16 v[96:111], v[136:139], v[154:157], v[96:111]
	ds_read_b64_tr_b16 v[150:151], v145 offset:16896
	ds_read_b64_tr_b16 v[152:153], v145 offset:20992
	s_waitcnt lgkmcnt(12)
	v_mfma_f32_32x32x16_bf16 v[80:95], v[136:139], v[192:195], v[80:95]
	ds_read_b64_tr_b16 v[154:155], v145 offset:17408
	ds_read_b64_tr_b16 v[156:157], v145 offset:21504
	s_waitcnt lgkmcnt(12)
	v_mfma_f32_32x32x16_bf16 v[64:79], v[136:139], v[196:199], v[64:79]
	ds_read_b64_tr_b16 v[192:193], v145 offset:17920
	ds_read_b64_tr_b16 v[194:195], v145 offset:22016
	s_waitcnt lgkmcnt(12)
	v_mfma_f32_32x32x16_bf16 v[48:63], v[136:139], v[200:203], v[48:63]
	ds_read_b64_tr_b16 v[196:197], v145 offset:18432
	ds_read_b64_tr_b16 v[198:199], v145 offset:22528
	s_waitcnt lgkmcnt(12)
	v_mfma_f32_32x32x16_bf16 v[32:47], v[136:139], v[204:207], v[32:47]
	ds_read_b64_tr_b16 v[200:201], v145 offset:18944
	ds_read_b64_tr_b16 v[202:203], v145 offset:23040
	s_waitcnt lgkmcnt(12)
	v_mfma_f32_32x32x16_bf16 v[16:31], v[136:139], v[232:235], v[16:31]
	ds_read_b64_tr_b16 v[204:205], v145 offset:19456
	ds_read_b64_tr_b16 v[206:207], v145 offset:23552
	s_waitcnt lgkmcnt(12)
	v_mfma_f32_32x32x16_bf16 v[0:15], v[132:135], v[146:149], v[0:15]
	ds_read_b64_tr_b16 v[232:233], v145 offset:19968
	ds_read_b64_tr_b16 v[234:235], v145 offset:24064
	s_waitcnt lgkmcnt(12)
	v_mfma_f32_32x32x16_bf16 v[112:127], v[132:135], v[150:153], v[112:127]
	ds_read_b64_tr_b16 v[146:147], v145 offset:24576
	ds_read_b64_tr_b16 v[148:149], v145 offset:28672
	s_waitcnt lgkmcnt(12)
	v_mfma_f32_32x32x16_bf16 v[96:111], v[132:135], v[154:157], v[96:111]
	ds_read_b64_tr_b16 v[150:151], v145 offset:25088
	ds_read_b64_tr_b16 v[152:153], v145 offset:29184
	s_waitcnt lgkmcnt(12)
	v_mfma_f32_32x32x16_bf16 v[80:95], v[132:135], v[192:195], v[80:95]
	ds_read_b64_tr_b16 v[154:155], v145 offset:25600
	ds_read_b64_tr_b16 v[156:157], v145 offset:29696
	s_waitcnt lgkmcnt(12)
	v_mfma_f32_32x32x16_bf16 v[64:79], v[132:135], v[196:199], v[64:79]
	ds_read_b64_tr_b16 v[192:193], v145 offset:26112
	ds_read_b64_tr_b16 v[194:195], v145 offset:30208
	s_waitcnt lgkmcnt(12)
	v_mfma_f32_32x32x16_bf16 v[48:63], v[132:135], v[200:203], v[48:63]
	ds_read_b64_tr_b16 v[196:197], v145 offset:26624
	ds_read_b64_tr_b16 v[198:199], v145 offset:30720
	s_waitcnt lgkmcnt(12)
	v_mfma_f32_32x32x16_bf16 v[32:47], v[132:135], v[204:207], v[32:47]
	ds_read_b64_tr_b16 v[200:201], v145 offset:27136
	ds_read_b64_tr_b16 v[202:203], v145 offset:31232
	s_waitcnt lgkmcnt(12)
	v_mfma_f32_32x32x16_bf16 v[16:31], v[132:135], v[232:235], v[16:31]
	ds_read_b64_tr_b16 v[204:205], v145 offset:27648
	ds_read_b64_tr_b16 v[206:207], v145 offset:31744
	s_waitcnt lgkmcnt(12)
	v_mfma_f32_32x32x16_bf16 v[0:15], v[140:143], v[146:149], v[0:15]
	ds_read_b64_tr_b16 v[232:233], v145 offset:28160
	ds_read_b64_tr_b16 v[234:235], v145 offset:32256
	s_waitcnt lgkmcnt(12)
	v_mfma_f32_32x32x16_bf16 v[112:127], v[140:143], v[150:153], v[112:127]
	s_waitcnt lgkmcnt(10)
	v_mfma_f32_32x32x16_bf16 v[96:111], v[140:143], v[154:157], v[96:111]
	s_waitcnt lgkmcnt(8)
	v_mfma_f32_32x32x16_bf16 v[80:95], v[140:143], v[192:195], v[80:95]
	s_waitcnt lgkmcnt(6)
	v_mfma_f32_32x32x16_bf16 v[64:79], v[140:143], v[196:199], v[64:79]
	s_add_i32 s4, s80, 1
	s_cmp_lg_u32 s80, 2
	s_cselect_b32 s80, s4, 0
	s_add_i32 s4, s78, 1
	s_cmp_lg_u32 s78, 2
	s_cselect_b32 s78, s4, 0
	s_add_u32 s22, s22, 0x20000
	s_waitcnt lgkmcnt(4)
	v_mfma_f32_32x32x16_bf16 v[48:63], v[140:143], v[200:203], v[48:63]
	s_addc_u32 s23, s23, 0
	s_add_i32 s86, s86, 1
	s_cmp_eq_u32 s22, 0x800000
	s_waitcnt lgkmcnt(2)
	v_mfma_f32_32x32x16_bf16 v[32:47], v[140:143], v[204:207], v[32:47]
	s_waitcnt lgkmcnt(0)
	v_mfma_f32_32x32x16_bf16 v[16:31], v[140:143], v[232:235], v[16:31]
	s_cbranch_scc1 .LBB0_914
	v_mov_b32_e32 v232, v144
	s_cmp_eq_u32 s22, 0x7e0000
	s_mov_b64 s[4:5], -1
	s_cbranch_scc1 .LBB0_903
